# final-phase output stores write-through (sc1) so the end-of-kernel L2 writeback is small
# baseline (speedup 1.0000x reference)
.LBB0_3315:
	v_lshl_or_b32 v144, s47, 8, v154
	v_lshl_add_u32 v146, s46, 8, v152
	v_ashrrev_i32_e32 v145, 31, v144
	v_add_u32_e32 v150, 0x100, v146
	v_lshlrev_b64 v[144:145], 2, v[144:145]
	v_ashrrev_i32_e32 v151, 31, v150
	v_lshl_add_u64 v[148:149], s[10:11], 0, v[144:145]
	v_lshlrev_b64 v[150:151], 12, v[150:151]
	global_load_dwordx4 v[158:161], v[148:149], off
	v_lshl_add_u64 v[150:151], s[6:7], 0, v[150:151]
	v_lshl_add_u64 v[178:179], v[150:151], 0, v[144:145]
	global_load_dwordx4 v[162:165], v[178:179], off
	global_load_dwordx4 v[166:169], v[148:149], off offset:16
	v_ashrrev_i32_e32 v147, 31, v146
	v_lshlrev_b64 v[150:151], 12, v[146:147]
	v_lshl_add_u64 v[150:151], s[4:5], 0, v[150:151]
	global_load_dwordx4 v[170:173], v[148:149], off offset:528
	global_load_dwordx4 v[174:177], v[148:149], off offset:512
	v_lshl_add_u64 v[180:181], v[150:151], 0, v[144:145]
	s_and_b64 vcc, exec, s[0:1]
	s_mov_b64 s[0:1], -1
	s_waitcnt vmcnt(0)
	v_pk_mul_f32 v[148:149], v[160:161], 0.5 op_sel_hi:[1,0]
	v_pk_mul_f32 v[150:151], v[158:159], 0.5 op_sel_hi:[1,0]
	v_pk_fma_f32 v[126:127], v[126:127], v[148:149], v[164:165]
	v_pk_fma_f32 v[124:125], v[124:125], v[150:151], v[162:163]
	global_store_dwordx4 v[180:181], v[124:127], off sc1
	global_load_dwordx4 v[158:161], v[178:179], off offset:16
	s_nop 0
	v_pk_mul_f32 v[124:125], v[168:169], 0.5 op_sel_hi:[1,0]
	v_pk_mul_f32 v[126:127], v[166:167], 0.5 op_sel_hi:[1,0]
	s_waitcnt vmcnt(0)
	v_pk_fma_f32 v[122:123], v[122:123], v[124:125], v[160:161]
	v_pk_fma_f32 v[120:121], v[120:121], v[126:127], v[158:159]
	global_store_dwordx4 v[180:181], v[120:123], off offset:16 sc1
	global_load_dwordx4 v[158:161], v[178:179], off offset:512
	s_nop 0
	v_pk_mul_f32 v[120:121], v[176:177], 0.5 op_sel_hi:[1,0]
	v_pk_mul_f32 v[122:123], v[174:175], 0.5 op_sel_hi:[1,0]
	s_waitcnt vmcnt(0)
	v_pk_fma_f32 v[118:119], v[118:119], v[120:121], v[160:161]
	v_pk_fma_f32 v[116:117], v[116:117], v[122:123], v[158:159]
	global_store_dwordx4 v[180:181], v[116:119], off offset:512 sc1
	global_load_dwordx4 v[158:161], v[178:179], off offset:528
	s_nop 0
	v_add_u32_e32 v116, 0x110, v146
	v_ashrrev_i32_e32 v117, 31, v116
	v_lshlrev_b64 v[116:117], 12, v[116:117]
	v_lshl_add_u64 v[116:117], s[6:7], 0, v[116:117]
	v_lshl_add_u64 v[162:163], v[116:117], 0, v[144:145]
	v_pk_mul_f32 v[116:117], v[172:173], 0.5 op_sel_hi:[1,0]
	v_pk_mul_f32 v[118:119], v[170:171], 0.5 op_sel_hi:[1,0]
	s_waitcnt vmcnt(0)
	v_pk_fma_f32 v[110:111], v[110:111], v[116:117], v[160:161]
	v_pk_fma_f32 v[108:109], v[108:109], v[118:119], v[158:159]
	global_store_dwordx4 v[180:181], v[108:111], off offset:528 sc1
	global_load_dwordx4 v[108:111], v[162:163], off
	v_or_b32_e32 v158, 16, v146
	v_ashrrev_i32_e32 v159, 31, v158
	v_lshlrev_b64 v[158:159], 12, v[158:159]
	v_lshl_add_u64 v[158:159], s[4:5], 0, v[158:159]
	v_lshl_add_u64 v[158:159], v[158:159], 0, v[144:145]
	s_waitcnt vmcnt(0)
	v_pk_fma_f32 v[110:111], v[114:115], v[148:149], v[110:111]
	v_pk_fma_f32 v[108:109], v[112:113], v[150:151], v[108:109]
	global_store_dwordx4 v[158:159], v[108:111], off sc1
	global_load_dwordx4 v[108:111], v[162:163], off offset:16
	s_waitcnt vmcnt(0)
	v_pk_fma_f32 v[106:107], v[106:107], v[124:125], v[110:111]
	v_pk_fma_f32 v[104:105], v[104:105], v[126:127], v[108:109]
	global_store_dwordx4 v[158:159], v[104:107], off offset:16 sc1
	global_load_dwordx4 v[104:107], v[162:163], off offset:512
	s_waitcnt vmcnt(0)
	v_pk_fma_f32 v[102:103], v[102:103], v[120:121], v[106:107]
	v_pk_fma_f32 v[100:101], v[100:101], v[122:123], v[104:105]
	global_store_dwordx4 v[158:159], v[100:103], off offset:512 sc1
	global_load_dwordx4 v[100:103], v[162:163], off offset:528
	v_add_u32_e32 v104, 0x120, v146
	v_ashrrev_i32_e32 v105, 31, v104
	v_lshlrev_b64 v[104:105], 12, v[104:105]
	v_lshl_add_u64 v[104:105], s[6:7], 0, v[104:105]
	v_lshl_add_u64 v[104:105], v[104:105], 0, v[144:145]
	s_waitcnt vmcnt(0)
	v_pk_fma_f32 v[94:95], v[94:95], v[116:117], v[102:103]
	v_pk_fma_f32 v[92:93], v[92:93], v[118:119], v[100:101]
	global_store_dwordx4 v[158:159], v[92:95], off offset:528 sc1
	global_load_dwordx4 v[92:95], v[104:105], off
	v_or_b32_e32 v100, 32, v146
	v_ashrrev_i32_e32 v101, 31, v100
	v_lshlrev_b64 v[100:101], 12, v[100:101]
	v_lshl_add_u64 v[100:101], s[4:5], 0, v[100:101]
	v_lshl_add_u64 v[100:101], v[100:101], 0, v[144:145]
	s_waitcnt vmcnt(0)
	v_pk_fma_f32 v[94:95], v[98:99], v[148:149], v[94:95]
	v_pk_fma_f32 v[92:93], v[96:97], v[150:151], v[92:93]
	global_store_dwordx4 v[100:101], v[92:95], off sc1
	global_load_dwordx4 v[92:95], v[104:105], off offset:16
	s_waitcnt vmcnt(0)
	v_pk_fma_f32 v[90:91], v[90:91], v[124:125], v[94:95]
	v_pk_fma_f32 v[88:89], v[88:89], v[126:127], v[92:93]
	global_store_dwordx4 v[100:101], v[88:91], off offset:16 sc1
	global_load_dwordx4 v[88:91], v[104:105], off offset:512
	s_waitcnt vmcnt(0)
	v_pk_fma_f32 v[86:87], v[86:87], v[120:121], v[90:91]
	v_pk_fma_f32 v[84:85], v[84:85], v[122:123], v[88:89]
	global_store_dwordx4 v[100:101], v[84:87], off offset:512 sc1
	global_load_dwordx4 v[84:87], v[104:105], off offset:528
	v_add_u32_e32 v88, 0x130, v146
	v_ashrrev_i32_e32 v89, 31, v88
	v_lshlrev_b64 v[88:89], 12, v[88:89]
	v_lshl_add_u64 v[88:89], s[6:7], 0, v[88:89]
	v_lshl_add_u64 v[88:89], v[88:89], 0, v[144:145]
	s_waitcnt vmcnt(0)
	v_pk_fma_f32 v[78:79], v[78:79], v[116:117], v[86:87]
	v_pk_fma_f32 v[76:77], v[76:77], v[118:119], v[84:85]
	global_store_dwordx4 v[100:101], v[76:79], off offset:528 sc1
	global_load_dwordx4 v[76:79], v[88:89], off
	v_or_b32_e32 v84, 48, v146
	v_ashrrev_i32_e32 v85, 31, v84
	v_lshlrev_b64 v[84:85], 12, v[84:85]
	v_lshl_add_u64 v[84:85], s[4:5], 0, v[84:85]
	v_lshl_add_u64 v[84:85], v[84:85], 0, v[144:145]
	s_waitcnt vmcnt(0)
	v_pk_fma_f32 v[78:79], v[82:83], v[148:149], v[78:79]
	v_pk_fma_f32 v[76:77], v[80:81], v[150:151], v[76:77]
	global_store_dwordx4 v[84:85], v[76:79], off sc1
	global_load_dwordx4 v[76:79], v[88:89], off offset:16
	s_waitcnt vmcnt(0)
	v_pk_fma_f32 v[74:75], v[74:75], v[124:125], v[78:79]
	v_pk_fma_f32 v[72:73], v[72:73], v[126:127], v[76:77]
	global_store_dwordx4 v[84:85], v[72:75], off offset:16 sc1
	global_load_dwordx4 v[72:75], v[88:89], off offset:512
	s_waitcnt vmcnt(0)
	v_pk_fma_f32 v[70:71], v[70:71], v[120:121], v[74:75]
	v_pk_fma_f32 v[68:69], v[68:69], v[122:123], v[72:73]
	global_store_dwordx4 v[84:85], v[68:71], off offset:512 sc1
	global_load_dwordx4 v[68:71], v[88:89], off offset:528
	v_add_u32_e32 v72, 0x180, v146
	v_ashrrev_i32_e32 v73, 31, v72
	v_lshlrev_b64 v[72:73], 12, v[72:73]
	v_lshl_add_u64 v[72:73], s[6:7], 0, v[72:73]
	v_lshl_add_u64 v[72:73], v[72:73], 0, v[144:145]
	s_waitcnt vmcnt(0)
	v_pk_fma_f32 v[66:67], v[66:67], v[116:117], v[70:71]
	v_pk_fma_f32 v[64:65], v[64:65], v[118:119], v[68:69]
	global_store_dwordx4 v[84:85], v[64:67], off offset:528 sc1
	global_load_dwordx4 v[64:67], v[72:73], off
	v_add_u32_e32 v68, 0x80, v146
	v_ashrrev_i32_e32 v69, 31, v68
	v_lshlrev_b64 v[68:69], 12, v[68:69]
	v_lshl_add_u64 v[68:69], s[4:5], 0, v[68:69]
	v_lshl_add_u64 v[68:69], v[68:69], 0, v[144:145]
	s_waitcnt vmcnt(0)
	v_pk_fma_f32 v[62:63], v[62:63], v[148:149], v[66:67]
	v_pk_fma_f32 v[60:61], v[60:61], v[150:151], v[64:65]
	global_store_dwordx4 v[68:69], v[60:63], off sc1
	global_load_dwordx4 v[60:63], v[72:73], off offset:16
	s_waitcnt vmcnt(0)
	v_pk_fma_f32 v[58:59], v[58:59], v[124:125], v[62:63]
	v_pk_fma_f32 v[56:57], v[56:57], v[126:127], v[60:61]
	global_store_dwordx4 v[68:69], v[56:59], off offset:16 sc1
	global_load_dwordx4 v[56:59], v[72:73], off offset:512
	s_waitcnt vmcnt(0)
	v_pk_fma_f32 v[54:55], v[54:55], v[120:121], v[58:59]
	v_pk_fma_f32 v[52:53], v[52:53], v[122:123], v[56:57]
	global_store_dwordx4 v[68:69], v[52:55], off offset:512 sc1
	global_load_dwordx4 v[52:55], v[72:73], off offset:528
	v_add_u32_e32 v56, 0x190, v146
	v_ashrrev_i32_e32 v57, 31, v56
	v_lshlrev_b64 v[56:57], 12, v[56:57]
	v_lshl_add_u64 v[56:57], s[6:7], 0, v[56:57]
	v_lshl_add_u64 v[56:57], v[56:57], 0, v[144:145]
	s_waitcnt vmcnt(0)
	v_pk_fma_f32 v[46:47], v[46:47], v[116:117], v[54:55]
	v_pk_fma_f32 v[44:45], v[44:45], v[118:119], v[52:53]
	global_store_dwordx4 v[68:69], v[44:47], off offset:528 sc1
	global_load_dwordx4 v[44:47], v[56:57], off
	v_add_u32_e32 v52, 0x90, v146
	v_ashrrev_i32_e32 v53, 31, v52
	v_lshlrev_b64 v[52:53], 12, v[52:53]
	v_lshl_add_u64 v[52:53], s[4:5], 0, v[52:53]
	v_lshl_add_u64 v[52:53], v[52:53], 0, v[144:145]
	s_waitcnt vmcnt(0)
	v_pk_fma_f32 v[46:47], v[50:51], v[148:149], v[46:47]
	v_pk_fma_f32 v[44:45], v[48:49], v[150:151], v[44:45]
	global_store_dwordx4 v[52:53], v[44:47], off sc1
	global_load_dwordx4 v[44:47], v[56:57], off offset:16
	s_waitcnt vmcnt(0)
	v_pk_fma_f32 v[42:43], v[42:43], v[124:125], v[46:47]
	v_pk_fma_f32 v[40:41], v[40:41], v[126:127], v[44:45]
	global_store_dwordx4 v[52:53], v[40:43], off offset:16 sc1
	global_load_dwordx4 v[40:43], v[56:57], off offset:512
	s_waitcnt vmcnt(0)
	v_pk_fma_f32 v[38:39], v[38:39], v[120:121], v[42:43]
	v_pk_fma_f32 v[36:37], v[36:37], v[122:123], v[40:41]
	global_store_dwordx4 v[52:53], v[36:39], off offset:512 sc1
	global_load_dwordx4 v[36:39], v[56:57], off offset:528
	v_add_u32_e32 v40, 0x1a0, v146
	v_ashrrev_i32_e32 v41, 31, v40
	v_lshlrev_b64 v[40:41], 12, v[40:41]
	v_lshl_add_u64 v[40:41], s[6:7], 0, v[40:41]
	v_lshl_add_u64 v[40:41], v[40:41], 0, v[144:145]
	s_waitcnt vmcnt(0)
	v_pk_fma_f32 v[30:31], v[30:31], v[116:117], v[38:39]
	v_pk_fma_f32 v[28:29], v[28:29], v[118:119], v[36:37]
	global_store_dwordx4 v[52:53], v[28:31], off offset:528 sc1
	global_load_dwordx4 v[28:31], v[40:41], off
	v_add_u32_e32 v36, 0xa0, v146
	v_ashrrev_i32_e32 v37, 31, v36
	v_lshlrev_b64 v[36:37], 12, v[36:37]
	v_lshl_add_u64 v[36:37], s[4:5], 0, v[36:37]
	v_lshl_add_u64 v[36:37], v[36:37], 0, v[144:145]
	s_waitcnt vmcnt(0)
	v_pk_fma_f32 v[30:31], v[34:35], v[148:149], v[30:31]
	v_pk_fma_f32 v[28:29], v[32:33], v[150:151], v[28:29]
	global_store_dwordx4 v[36:37], v[28:31], off sc1
	global_load_dwordx4 v[28:31], v[40:41], off offset:16
	s_waitcnt vmcnt(0)
	v_pk_fma_f32 v[26:27], v[26:27], v[124:125], v[30:31]
	v_pk_fma_f32 v[24:25], v[24:25], v[126:127], v[28:29]
	global_store_dwordx4 v[36:37], v[24:27], off offset:16 sc1
	global_load_dwordx4 v[24:27], v[40:41], off offset:512
	s_waitcnt vmcnt(0)
	v_pk_fma_f32 v[22:23], v[22:23], v[120:121], v[26:27]
	v_pk_fma_f32 v[20:21], v[20:21], v[122:123], v[24:25]
	global_store_dwordx4 v[36:37], v[20:23], off offset:512 sc1
	global_load_dwordx4 v[20:23], v[40:41], off offset:528
	v_add_u32_e32 v24, 0x1b0, v146
	v_ashrrev_i32_e32 v25, 31, v24
	v_lshlrev_b64 v[24:25], 12, v[24:25]
	v_lshl_add_u64 v[24:25], s[6:7], 0, v[24:25]
	v_lshl_add_u64 v[24:25], v[24:25], 0, v[144:145]
	s_waitcnt vmcnt(0)
	v_pk_fma_f32 v[14:15], v[14:15], v[116:117], v[22:23]
	v_pk_fma_f32 v[12:13], v[12:13], v[118:119], v[20:21]
	global_store_dwordx4 v[36:37], v[12:15], off offset:528 sc1
	global_load_dwordx4 v[12:15], v[24:25], off
	v_add_u32_e32 v20, 0xb0, v146
	v_ashrrev_i32_e32 v21, 31, v20
	v_lshlrev_b64 v[20:21], 12, v[20:21]
	v_lshl_add_u64 v[20:21], s[4:5], 0, v[20:21]
	v_lshl_add_u64 v[20:21], v[20:21], 0, v[144:145]
	s_waitcnt vmcnt(0)
	v_pk_fma_f32 v[14:15], v[18:19], v[148:149], v[14:15]
	v_pk_fma_f32 v[12:13], v[16:17], v[150:151], v[12:13]
	global_store_dwordx4 v[20:21], v[12:15], off sc1
	global_load_dwordx4 v[12:15], v[24:25], off offset:16
	s_waitcnt vmcnt(0)
	v_pk_fma_f32 v[10:11], v[10:11], v[124:125], v[14:15]
	v_pk_fma_f32 v[8:9], v[8:9], v[126:127], v[12:13]
	global_store_dwordx4 v[20:21], v[8:11], off offset:16 sc1
	global_load_dwordx4 v[8:11], v[24:25], off offset:512
	s_waitcnt vmcnt(0)
	v_pk_fma_f32 v[6:7], v[6:7], v[120:121], v[10:11]
	v_pk_fma_f32 v[4:5], v[4:5], v[122:123], v[8:9]
	global_store_dwordx4 v[20:21], v[4:7], off offset:512 sc1
	global_load_dwordx4 v[4:7], v[24:25], off offset:528
	s_waitcnt vmcnt(0)
	v_pk_fma_f32 v[2:3], v[2:3], v[116:117], v[6:7]
	v_pk_fma_f32 v[0:1], v[0:1], v[118:119], v[4:5]
	global_store_dwordx4 v[20:21], v[0:3], off offset:528 sc1
	s_cbranch_vccnz .LBB0_3304
	s_andn2_b64 vcc, exec, s[8:9]
	s_cbranch_vccnz .LBB0_3303
	s_barrier
	s_branch .LBB0_3303
